# stack + P3: dropped a full vmcnt drain in front of the list-length load (it serialised behind the K/V prefetch)
# speedup vs baseline: 1.0390x; 1.0094x over previous
.LBB0_383:
	s_add_i32 s0, s42, s3
	s_ashr_i32 s1, s0, 31
	s_lshl_b64 s[0:1], s[0:1], 2
	s_add_u32 s0, s20, s0
	s_addc_u32 s1, s21, s1
	v_mov_b32_e32 v195, 0
	global_load_dword v0, v195, s[0:1]
	s_add_i32 s1, s42, -1
	s_mul_i32 s1, s1, s42
	s_mul_i32 s0, s42, 31
	s_lshr_b32 s42, s1, 31
	s_add_i32 s1, s1, s42
	s_lshr_b32 s1, s1, 1
	s_sub_i32 s0, s0, s1
	s_lshl_b32 s0, s0, 8
	s_ashr_i32 s1, s0, 31
	s_lshl_b64 s[0:1], s[0:1], 2
	s_mov_b64 s[82:83], 0
	s_waitcnt vmcnt(0)
	v_readfirstlane_b32 s42, v0
	s_add_i32 s57, s42, 0x100
	s_addk_i32 s42, 0x11f
	s_ashr_i32 s42, s42, 5
	s_add_u32 s78, s55, s0
	s_addc_u32 s79, s41, s1
	s_cmp_ge_i32 s27, s42
	s_cbranch_scc1 .LBB0_385
	v_cmp_gt_i32_e32 vcc, s57, v200
	s_and_b64 s[82:83], vcc, exec
	s_nop 0
	v_cndmask_b32_e32 v162, 0, v201, vcc
	v_lshl_add_u64 v[0:1], v[162:163], 2, s[78:79]
	global_load_dword v195, v[0:1], off
